# SSD state update: all 41 LDS reads issued up front into distinct registers, MFMAs back to back with counted lgkmcnt waits (both direction loops); on top of v53
# speedup vs baseline: 1.0080x; 1.0080x over previous
.LBB0_1009:
	s_nop 0
	v_mov_b32_e32 v243, s54
	ds_read_b32 v242, v243
	ds_read_b64_tr_b16 v[56:57], v162 offset:34816
	ds_read_b64_tr_b16 v[58:59], v162 offset:35904
	ds_read_b64_tr_b16 v[74:75], v163
	ds_read_b64_tr_b16 v[76:77], v163 offset:576
	ds_read_b64_tr_b16 v[78:79], v163 offset:32
	ds_read_b64_tr_b16 v[80:81], v163 offset:608
	ds_read_b64_tr_b16 v[82:83], v163 offset:64
	ds_read_b64_tr_b16 v[84:85], v163 offset:640
	ds_read_b64_tr_b16 v[86:87], v163 offset:96
	ds_read_b64_tr_b16 v[88:89], v163 offset:672
	ds_read_b64_tr_b16 v[60:61], v162 offset:43520
	ds_read_b64_tr_b16 v[62:63], v162 offset:44608
	ds_read_b64_tr_b16 v[90:91], v163 offset:4608
	ds_read_b64_tr_b16 v[92:93], v163 offset:5184
	ds_read_b64_tr_b16 v[94:95], v163 offset:4640
	ds_read_b64_tr_b16 v[96:97], v163 offset:5216
	ds_read_b64_tr_b16 v[98:99], v163 offset:4672
	ds_read_b64_tr_b16 v[100:101], v163 offset:5248
	ds_read_b64_tr_b16 v[102:103], v163 offset:4704
	ds_read_b64_tr_b16 v[104:105], v163 offset:5280
	ds_read_b64_tr_b16 v[66:67], v162 offset:52224
	ds_read_b64_tr_b16 v[68:69], v162 offset:53312
	ds_read_b64_tr_b16 v[106:107], v163 offset:9216
	ds_read_b64_tr_b16 v[108:109], v163 offset:9792
	ds_read_b64_tr_b16 v[110:111], v163 offset:9248
	ds_read_b64_tr_b16 v[112:113], v163 offset:9824
	ds_read_b64_tr_b16 v[114:115], v163 offset:9280
	ds_read_b64_tr_b16 v[116:117], v163 offset:9856
	ds_read_b64_tr_b16 v[118:119], v163 offset:9312
	ds_read_b64_tr_b16 v[120:121], v163 offset:9888
	ds_read_b64_tr_b16 v[70:71], v162 offset:60928
	ds_read_b64_tr_b16 v[72:73], v162 offset:62016
	ds_read_b64_tr_b16 v[122:123], v163 offset:13824
	ds_read_b64_tr_b16 v[124:125], v163 offset:14400
	ds_read_b64_tr_b16 v[126:127], v163 offset:13856
	ds_read_b64_tr_b16 v[128:129], v163 offset:14432
	ds_read_b64_tr_b16 v[238:239], v163 offset:13888
	ds_read_b64_tr_b16 v[240:241], v163 offset:14464
	ds_read_b64_tr_b16 v[244:245], v163 offset:13920
	ds_read_b64_tr_b16 v[246:247], v163 offset:14496
	s_waitcnt lgkmcnt(15)
	v_mul_f32_e32 v242, 0x3fb8aa3b, v242
	v_exp_f32_e32 v248, v242
	s_nop 0
	v_pk_mul_f32 v[42:43], v[42:43], v[248:249] op_sel_hi:[1,0]
	v_pk_mul_f32 v[40:41], v[40:41], v[248:249] op_sel_hi:[1,0]
	v_pk_mul_f32 v[46:47], v[46:47], v[248:249] op_sel_hi:[1,0]
	v_pk_mul_f32 v[44:45], v[44:45], v[248:249] op_sel_hi:[1,0]
	v_pk_mul_f32 v[50:51], v[50:51], v[248:249] op_sel_hi:[1,0]
	v_pk_mul_f32 v[48:49], v[48:49], v[248:249] op_sel_hi:[1,0]
	v_pk_mul_f32 v[54:55], v[54:55], v[248:249] op_sel_hi:[1,0]
	v_pk_mul_f32 v[52:53], v[52:53], v[248:249] op_sel_hi:[1,0]
	s_and_b64 s[22:23], s[78:79], exec
	s_mov_b32 s22, 0x1e400
	s_cselect_b32 s22, s22, 0x1a000
	s_cmp_eq_u32 s47, 34
	v_mfma_f32_16x16x32_bf16 v[40:43], v[56:59], v[74:77], v[40:43]
	v_mfma_f32_16x16x32_bf16 v[44:47], v[56:59], v[78:81], v[44:47]
	v_mfma_f32_16x16x32_bf16 v[48:51], v[56:59], v[82:85], v[48:51]
	v_mfma_f32_16x16x32_bf16 v[52:55], v[56:59], v[86:89], v[52:55]
	v_mfma_f32_16x16x32_bf16 v[40:43], v[60:63], v[90:93], v[40:43]
	v_mfma_f32_16x16x32_bf16 v[44:47], v[60:63], v[94:97], v[44:47]
	v_mfma_f32_16x16x32_bf16 v[48:51], v[60:63], v[98:101], v[48:51]
	v_mfma_f32_16x16x32_bf16 v[52:55], v[60:63], v[102:105], v[52:55]
	v_mfma_f32_16x16x32_bf16 v[40:43], v[66:69], v[106:109], v[40:43]
	s_waitcnt lgkmcnt(14)
	v_mfma_f32_16x16x32_bf16 v[44:47], v[66:69], v[110:113], v[44:47]
	s_waitcnt lgkmcnt(12)
	v_mfma_f32_16x16x32_bf16 v[48:51], v[66:69], v[114:117], v[48:51]
	s_waitcnt lgkmcnt(10)
	v_mfma_f32_16x16x32_bf16 v[52:55], v[66:69], v[118:121], v[52:55]
	s_waitcnt lgkmcnt(6)
	v_mfma_f32_16x16x32_bf16 v[40:43], v[70:73], v[122:125], v[40:43]
	s_waitcnt lgkmcnt(4)
	v_mfma_f32_16x16x32_bf16 v[44:47], v[70:73], v[126:129], v[44:47]
	s_waitcnt lgkmcnt(2)
	v_mfma_f32_16x16x32_bf16 v[48:51], v[70:73], v[238:241], v[48:51]
	s_waitcnt lgkmcnt(0)
	v_mfma_f32_16x16x32_bf16 v[52:55], v[70:73], v[244:247], v[52:55]
	v_cvt_pk_bf16_f32 v56, v40, v41
	v_cvt_pk_bf16_f32 v57, v42, v43
	v_add_u32_e32 v58, s22, v151
	ds_write_b64 v58, v[56:57]
	v_cvt_pk_bf16_f32 v56, v44, v45
	v_cvt_pk_bf16_f32 v57, v46, v47
	ds_write_b64 v58, v[56:57] offset:4352
	v_cvt_pk_bf16_f32 v56, v48, v49
	v_cvt_pk_bf16_f32 v57, v50, v51
	ds_write_b64 v58, v[56:57] offset:8704
	v_cvt_pk_bf16_f32 v56, v52, v53
	v_cvt_pk_bf16_f32 v57, v54, v55
	ds_write_b64 v58, v[56:57] offset:13056
	s_cbranch_scc1 .LBB0_1116

.LBB0_1237:
	s_nop 0
	v_mov_b32_e32 v243, s35
	ds_read_b32 v242, v243 offset:508
	ds_read_b64_tr_b16 v[56:57], v163 offset:34816
	ds_read_b64_tr_b16 v[58:59], v163 offset:35904
	ds_read_b64_tr_b16 v[74:75], v164
	ds_read_b64_tr_b16 v[76:77], v164 offset:576
	ds_read_b64_tr_b16 v[78:79], v164 offset:32
	ds_read_b64_tr_b16 v[80:81], v164 offset:608
	ds_read_b64_tr_b16 v[82:83], v164 offset:64
	ds_read_b64_tr_b16 v[84:85], v164 offset:640
	ds_read_b64_tr_b16 v[86:87], v164 offset:96
	ds_read_b64_tr_b16 v[88:89], v164 offset:672
	ds_read_b64_tr_b16 v[60:61], v163 offset:43520
	ds_read_b64_tr_b16 v[62:63], v163 offset:44608
	ds_read_b64_tr_b16 v[90:91], v164 offset:4608
	ds_read_b64_tr_b16 v[92:93], v164 offset:5184
	ds_read_b64_tr_b16 v[94:95], v164 offset:4640
	ds_read_b64_tr_b16 v[96:97], v164 offset:5216
	ds_read_b64_tr_b16 v[98:99], v164 offset:4672
	ds_read_b64_tr_b16 v[100:101], v164 offset:5248
	ds_read_b64_tr_b16 v[102:103], v164 offset:4704
	ds_read_b64_tr_b16 v[104:105], v164 offset:5280
	ds_read_b64_tr_b16 v[66:67], v163 offset:52224
	ds_read_b64_tr_b16 v[68:69], v163 offset:53312
	ds_read_b64_tr_b16 v[106:107], v164 offset:9216
	ds_read_b64_tr_b16 v[108:109], v164 offset:9792
	ds_read_b64_tr_b16 v[110:111], v164 offset:9248
	ds_read_b64_tr_b16 v[112:113], v164 offset:9824
	ds_read_b64_tr_b16 v[114:115], v164 offset:9280
	ds_read_b64_tr_b16 v[116:117], v164 offset:9856
	ds_read_b64_tr_b16 v[118:119], v164 offset:9312
	ds_read_b64_tr_b16 v[120:121], v164 offset:9888
	ds_read_b64_tr_b16 v[70:71], v163 offset:60928
	ds_read_b64_tr_b16 v[72:73], v163 offset:62016
	ds_read_b64_tr_b16 v[122:123], v164 offset:13824
	ds_read_b64_tr_b16 v[124:125], v164 offset:14400
	ds_read_b64_tr_b16 v[126:127], v164 offset:13856
	ds_read_b64_tr_b16 v[128:129], v164 offset:14432
	ds_read_b64_tr_b16 v[238:239], v164 offset:13888
	ds_read_b64_tr_b16 v[240:241], v164 offset:14464
	ds_read_b64_tr_b16 v[244:245], v164 offset:13920
	ds_read_b64_tr_b16 v[246:247], v164 offset:14496
	s_waitcnt lgkmcnt(15)
	v_mul_f32_e32 v242, 0x3fb8aa3b, v242
	v_exp_f32_e32 v248, v242
	s_nop 0
	v_pk_mul_f32 v[42:43], v[42:43], v[248:249] op_sel_hi:[1,0]
	v_pk_mul_f32 v[40:41], v[40:41], v[248:249] op_sel_hi:[1,0]
	v_pk_mul_f32 v[46:47], v[46:47], v[248:249] op_sel_hi:[1,0]
	v_pk_mul_f32 v[44:45], v[44:45], v[248:249] op_sel_hi:[1,0]
	v_pk_mul_f32 v[50:51], v[50:51], v[248:249] op_sel_hi:[1,0]
	v_pk_mul_f32 v[48:49], v[48:49], v[248:249] op_sel_hi:[1,0]
	v_pk_mul_f32 v[54:55], v[54:55], v[248:249] op_sel_hi:[1,0]
	v_pk_mul_f32 v[52:53], v[52:53], v[248:249] op_sel_hi:[1,0]
	s_and_b64 s[20:21], s[22:23], exec
	s_mov_b32 s20, 0x1e400
	s_cselect_b32 s20, s20, 0x1a000
	s_cmp_eq_u32 s26, 34
	s_mov_b32 s83, 0x41a00000
	v_mfma_f32_16x16x32_bf16 v[40:43], v[56:59], v[74:77], v[40:43]
	v_mfma_f32_16x16x32_bf16 v[44:47], v[56:59], v[78:81], v[44:47]
	v_mfma_f32_16x16x32_bf16 v[48:51], v[56:59], v[82:85], v[48:51]
	v_mfma_f32_16x16x32_bf16 v[52:55], v[56:59], v[86:89], v[52:55]
	v_mfma_f32_16x16x32_bf16 v[40:43], v[60:63], v[90:93], v[40:43]
	v_mfma_f32_16x16x32_bf16 v[44:47], v[60:63], v[94:97], v[44:47]
	v_mfma_f32_16x16x32_bf16 v[48:51], v[60:63], v[98:101], v[48:51]
	v_mfma_f32_16x16x32_bf16 v[52:55], v[60:63], v[102:105], v[52:55]
	v_mfma_f32_16x16x32_bf16 v[40:43], v[66:69], v[106:109], v[40:43]
	s_waitcnt lgkmcnt(14)
	v_mfma_f32_16x16x32_bf16 v[44:47], v[66:69], v[110:113], v[44:47]
	s_waitcnt lgkmcnt(12)
	v_mfma_f32_16x16x32_bf16 v[48:51], v[66:69], v[114:117], v[48:51]
	s_waitcnt lgkmcnt(10)
	v_mfma_f32_16x16x32_bf16 v[52:55], v[66:69], v[118:121], v[52:55]
	s_waitcnt lgkmcnt(6)
	v_mfma_f32_16x16x32_bf16 v[40:43], v[70:73], v[122:125], v[40:43]
	s_waitcnt lgkmcnt(4)
	v_mfma_f32_16x16x32_bf16 v[44:47], v[70:73], v[126:129], v[44:47]
	s_waitcnt lgkmcnt(2)
	v_mfma_f32_16x16x32_bf16 v[48:51], v[70:73], v[238:241], v[48:51]
	s_waitcnt lgkmcnt(0)
	v_mfma_f32_16x16x32_bf16 v[52:55], v[70:73], v[244:247], v[52:55]
	v_cvt_pk_bf16_f32 v56, v40, v41
	v_cvt_pk_bf16_f32 v57, v42, v43
	v_add_u32_e32 v58, s20, v154
	ds_write_b64 v58, v[56:57]
	v_cvt_pk_bf16_f32 v56, v44, v45
	v_cvt_pk_bf16_f32 v57, v46, v47
	ds_write_b64 v58, v[56:57] offset:4352
	v_cvt_pk_bf16_f32 v56, v48, v49
	v_cvt_pk_bf16_f32 v57, v50, v51
	ds_write_b64 v58, v[56:57] offset:8704
	v_cvt_pk_bf16_f32 v56, v52, v53
	v_cvt_pk_bf16_f32 v57, v54, v55
	ds_write_b64 v58, v[56:57] offset:13056
	s_cbranch_scc1 .LBB0_1240
	s_mov_b32 s34, s26
	s_branch .LBB0_1132
